# adds: ssd_sample state stores and P1 kv-window stores issued as plain (non-nt) stores so the in-order vmcnt waits behind them are not gated by slow write acks
# speedup vs baseline: 1.0116x; 1.0116x over previous
.LBB0_150:
	s_andn2_b64 vcc, exec, s[8:9]
	s_cbranch_vccnz .LBB0_157
	s_or_b32 s8, s90, s93
	v_pk_mul_f32 v[128:129], v[126:127], s[44:45] op_sel_hi:[1,0]
	v_pk_mul_f32 v[130:131], v[124:125], s[44:45] op_sel_hi:[1,0]
	v_pk_mul_f32 v[180:181], v[122:123], s[44:45] op_sel_hi:[1,0]
	v_pk_mul_f32 v[182:183], v[120:121], s[44:45] op_sel_hi:[1,0]
	s_ashr_i32 s9, s8, 31
	v_cndmask_b32_e64 v181, v123, v181, s[6:7]
	v_cndmask_b32_e64 v180, v122, v180, s[6:7]
	v_cndmask_b32_e64 v183, v121, v183, s[6:7]
	v_cndmask_b32_e64 v182, v120, v182, s[6:7]
	v_cndmask_b32_e64 v129, v127, v129, s[6:7]
	v_cndmask_b32_e64 v184, v126, v128, s[6:7]
	v_cndmask_b32_e64 v128, v125, v131, s[6:7]
	v_cndmask_b32_e64 v130, v124, v130, s[6:7]
	v_cvt_pk_bf16_f32 v128, v130, v128
	v_cvt_pk_bf16_f32 v129, v184, v129
	v_cvt_pk_bf16_f32 v130, v182, v183
	v_cvt_pk_bf16_f32 v131, v180, v181
	s_lshl_b64 s[8:9], s[8:9], 19
	s_andn2_b64 vcc, exec, s[60:61]
	s_mov_b64 s[10:11], -1
	s_cbranch_vccnz .LBB0_155
	s_and_b64 s[10:11], s[56:57], exec
	s_cselect_b32 s10, s86, s88
	s_cselect_b32 s11, s87, s89
	s_add_u32 s10, s10, s8
	s_addc_u32 s11, s11, s9
	v_lshlrev_b32_e32 v180, 1, v179
	v_mov_b32_e32 v181, v141
	v_lshl_add_u64 v[180:181], s[10:11], 0, v[180:181]
	v_lshlrev_b32_e32 v182, 1, v146
	v_mov_b32_e32 v183, v141
	v_lshl_add_u64 v[180:181], v[180:181], 0, v[182:183]
	global_store_dwordx4 v[180:181], v[128:131], off
	s_and_saveexec_b64 s[10:11], s[12:13]
	s_cbranch_execz .LBB0_154
	s_lshl_b32 s74, s47, 2
	s_add_u32 s74, s18, s74
	v_or_b32_e32 v180, s93, v158
	v_mov_b32_e32 v181, v159
	s_addc_u32 s75, s19, 0
	v_lshlrev_b64 v[180:181], 8, v[180:181]
	v_lshl_add_u64 v[180:181], s[74:75], 0, v[180:181]
	v_lshlrev_b32_e32 v182, 2, v146
	v_mov_b32_e32 v183, v141
	v_lshl_add_u64 v[180:181], v[180:181], 0, v[182:183]
	global_store_dwordx4 v[180:181], v[124:127], off
	global_store_dwordx4 v[180:181], v[120:123], off offset:16

.LBB0_172:
	s_andn2_b64 vcc, exec, s[14:15]
	s_cbranch_vccnz .LBB0_179
	s_or_b32 s14, s90, s94
	v_pk_mul_f32 v[120:121], v[118:119], s[44:45] op_sel_hi:[1,0]
	v_pk_mul_f32 v[122:123], v[116:117], s[44:45] op_sel_hi:[1,0]
	v_pk_mul_f32 v[124:125], v[114:115], s[44:45] op_sel_hi:[1,0]
	v_pk_mul_f32 v[126:127], v[112:113], s[44:45] op_sel_hi:[1,0]
	s_ashr_i32 s15, s14, 31
	v_cndmask_b32_e64 v125, v115, v125, s[6:7]
	v_cndmask_b32_e64 v124, v114, v124, s[6:7]
	v_cndmask_b32_e64 v127, v113, v127, s[6:7]
	v_cndmask_b32_e64 v126, v112, v126, s[6:7]
	v_cndmask_b32_e64 v121, v119, v121, s[6:7]
	v_cndmask_b32_e64 v128, v118, v120, s[6:7]
	v_cndmask_b32_e64 v120, v117, v123, s[6:7]
	v_cndmask_b32_e64 v122, v116, v122, s[6:7]
	v_cvt_pk_bf16_f32 v120, v122, v120
	v_cvt_pk_bf16_f32 v121, v128, v121
	v_cvt_pk_bf16_f32 v122, v126, v127
	v_cvt_pk_bf16_f32 v123, v124, v125
	s_lshl_b64 s[14:15], s[14:15], 19
	s_mov_b64 s[72:73], -1
	s_andn2_b64 vcc, exec, s[60:61]
	v_lshlrev_b32_e32 v124, 1, v179
	s_cbranch_vccnz .LBB0_177
	s_and_b64 s[72:73], s[56:57], exec
	s_cselect_b32 s72, s86, s88
	s_cselect_b32 s73, s87, s89
	s_add_u32 s72, s72, s14
	s_addc_u32 s73, s73, s15
	v_mov_b32_e32 v125, v141
	v_lshl_add_u64 v[126:127], s[72:73], 0, v[124:125]
	v_lshlrev_b32_e32 v128, 1, v150
	v_mov_b32_e32 v129, v141
	v_lshl_add_u64 v[126:127], v[126:127], 0, v[128:129]
	global_store_dwordx4 v[126:127], v[120:123], off
	s_and_saveexec_b64 s[72:73], s[12:13]
	s_cbranch_execz .LBB0_176
	s_lshl_b32 s12, s47, 2
	s_add_u32 s12, s18, s12
	v_or_b32_e32 v158, s94, v158
	s_addc_u32 s13, s19, 0
	v_lshlrev_b64 v[126:127], 8, v[158:159]
	v_lshl_add_u64 v[126:127], s[12:13], 0, v[126:127]
	v_lshlrev_b32_e32 v128, 2, v150
	v_mov_b32_e32 v129, v141
	v_lshl_add_u64 v[126:127], v[126:127], 0, v[128:129]
	global_store_dwordx4 v[126:127], v[116:119], off
	global_store_dwordx4 v[126:127], v[112:115], off offset:16

.LBB0_194:
	s_andn2_b64 vcc, exec, s[14:15]
	s_cbranch_vccnz .LBB0_201
	s_or_b32 s14, s90, s93
	v_pk_mul_f32 v[112:113], v[110:111], s[44:45] op_sel_hi:[1,0]
	v_pk_mul_f32 v[114:115], v[108:109], s[44:45] op_sel_hi:[1,0]
	v_pk_mul_f32 v[130:131], v[106:107], s[44:45] op_sel_hi:[1,0]
	v_pk_mul_f32 v[158:159], v[104:105], s[44:45] op_sel_hi:[1,0]
	s_ashr_i32 s15, s14, 31
	v_cndmask_b32_e64 v129, v107, v131, s[6:7]
	v_cndmask_b32_e64 v130, v106, v130, s[6:7]
	v_cndmask_b32_e64 v131, v105, v159, s[6:7]
	v_cndmask_b32_e64 v158, v104, v158, s[6:7]
	v_cndmask_b32_e64 v113, v111, v113, s[6:7]
	v_cndmask_b32_e64 v159, v110, v112, s[6:7]
	v_cndmask_b32_e64 v112, v109, v115, s[6:7]
	v_cndmask_b32_e64 v114, v108, v114, s[6:7]
	v_cvt_pk_bf16_f32 v112, v114, v112
	v_cvt_pk_bf16_f32 v113, v159, v113
	v_cvt_pk_bf16_f32 v114, v158, v131
	v_cvt_pk_bf16_f32 v115, v130, v129
	s_lshl_b64 s[14:15], s[14:15], 19
	s_andn2_b64 vcc, exec, s[60:61]
	s_mov_b64 s[72:73], -1
	s_cbranch_vccnz .LBB0_199
	s_and_b64 s[72:73], s[56:57], exec
	s_cselect_b32 s72, s86, s88
	s_cselect_b32 s71, s87, s89
	s_add_u32 s72, s72, s14
	s_addc_u32 s73, s71, s15
	v_lshlrev_b32_e32 v130, 1, v128
	v_mov_b32_e32 v131, v141
	v_lshl_add_u64 v[130:131], s[72:73], 0, v[130:131]
	v_lshlrev_b32_e32 v158, 1, v146
	v_mov_b32_e32 v159, v141
	v_lshl_add_u64 v[130:131], v[130:131], 0, v[158:159]
	global_store_dwordx4 v[130:131], v[112:115], off
	s_and_saveexec_b64 s[72:73], s[12:13]
	s_cbranch_execz .LBB0_198
	s_lshl_b32 s71, s47, 2
	s_add_u32 vcc_lo, s18, s71
	v_or_b32_e32 v130, s93, v116
	v_mov_b32_e32 v131, v117
	s_addc_u32 vcc_hi, s19, 0
	v_lshlrev_b64 v[130:131], 8, v[130:131]
	v_lshl_add_u64 v[130:131], vcc, 0, v[130:131]
	v_lshlrev_b32_e32 v158, 2, v146
	v_mov_b32_e32 v159, v141
	v_lshl_add_u64 v[130:131], v[130:131], 0, v[158:159]
	global_store_dwordx4 v[130:131], v[108:111], off
	global_store_dwordx4 v[130:131], v[104:107], off offset:16

.LBB0_216:
	s_andn2_b64 vcc, exec, s[14:15]
	s_cbranch_vccnz .LBB0_223
	s_or_b32 s14, s90, s94
	v_pk_mul_f32 v[104:105], v[102:103], s[44:45] op_sel_hi:[1,0]
	v_pk_mul_f32 v[106:107], v[100:101], s[44:45] op_sel_hi:[1,0]
	v_pk_mul_f32 v[108:109], v[98:99], s[44:45] op_sel_hi:[1,0]
	v_pk_mul_f32 v[110:111], v[96:97], s[44:45] op_sel_hi:[1,0]
	s_ashr_i32 s15, s14, 31
	v_cndmask_b32_e64 v109, v99, v109, s[6:7]
	v_cndmask_b32_e64 v108, v98, v108, s[6:7]
	v_cndmask_b32_e64 v111, v97, v111, s[6:7]
	v_cndmask_b32_e64 v110, v96, v110, s[6:7]
	v_cndmask_b32_e64 v105, v103, v105, s[6:7]
	v_cndmask_b32_e64 v112, v102, v104, s[6:7]
	v_cndmask_b32_e64 v104, v101, v107, s[6:7]
	v_cndmask_b32_e64 v106, v100, v106, s[6:7]
	v_cvt_pk_bf16_f32 v104, v106, v104
	v_cvt_pk_bf16_f32 v105, v112, v105
	v_cvt_pk_bf16_f32 v106, v110, v111
	v_cvt_pk_bf16_f32 v107, v108, v109
	s_lshl_b64 s[14:15], s[14:15], 19
	s_mov_b64 s[72:73], -1
	s_andn2_b64 vcc, exec, s[60:61]
	v_lshlrev_b32_e32 v108, 1, v128
	s_cbranch_vccnz .LBB0_221
	s_and_b64 s[72:73], s[56:57], exec
	s_cselect_b32 s72, s86, s88
	s_cselect_b32 s71, s87, s89
	s_add_u32 s72, s72, s14
	s_addc_u32 s73, s71, s15
	v_mov_b32_e32 v109, v141
	v_lshl_add_u64 v[110:111], s[72:73], 0, v[108:109]
	v_lshlrev_b32_e32 v112, 1, v150
	v_mov_b32_e32 v113, v141
	v_lshl_add_u64 v[110:111], v[110:111], 0, v[112:113]
	global_store_dwordx4 v[110:111], v[104:107], off
	s_and_saveexec_b64 s[72:73], s[12:13]
	s_cbranch_execz .LBB0_220
	s_lshl_b32 s12, s47, 2
	s_add_u32 s12, s18, s12
	v_or_b32_e32 v116, s94, v116
	s_addc_u32 s13, s19, 0
	v_lshlrev_b64 v[110:111], 8, v[116:117]
	v_lshl_add_u64 v[110:111], s[12:13], 0, v[110:111]
	v_lshlrev_b32_e32 v112, 2, v150
	v_mov_b32_e32 v113, v141
	v_lshl_add_u64 v[110:111], v[110:111], 0, v[112:113]
	global_store_dwordx4 v[110:111], v[100:103], off
	global_store_dwordx4 v[110:111], v[96:99], off offset:16

.LBB0_238:
	s_andn2_b64 vcc, exec, s[14:15]
	s_cbranch_vccnz .LBB0_245
	s_or_b32 s14, s90, s93
	v_pk_mul_f32 v[96:97], v[94:95], s[44:45] op_sel_hi:[1,0]
	v_pk_mul_f32 v[98:99], v[92:93], s[44:45] op_sel_hi:[1,0]
	v_pk_mul_f32 v[114:115], v[90:91], s[44:45] op_sel_hi:[1,0]
	v_pk_mul_f32 v[116:117], v[88:89], s[44:45] op_sel_hi:[1,0]
	s_ashr_i32 s15, s14, 31
	v_cndmask_b32_e64 v113, v91, v115, s[6:7]
	v_cndmask_b32_e64 v114, v90, v114, s[6:7]
	v_cndmask_b32_e64 v115, v89, v117, s[6:7]
	v_cndmask_b32_e64 v116, v88, v116, s[6:7]
	v_cndmask_b32_e64 v97, v95, v97, s[6:7]
	v_cndmask_b32_e64 v117, v94, v96, s[6:7]
	v_cndmask_b32_e64 v96, v93, v99, s[6:7]
	v_cndmask_b32_e64 v98, v92, v98, s[6:7]
	v_cvt_pk_bf16_f32 v96, v98, v96
	v_cvt_pk_bf16_f32 v97, v117, v97
	v_cvt_pk_bf16_f32 v98, v116, v115
	v_cvt_pk_bf16_f32 v99, v114, v113
	s_lshl_b64 s[14:15], s[14:15], 19
	s_andn2_b64 vcc, exec, s[60:61]
	s_mov_b64 s[72:73], -1
	s_cbranch_vccnz .LBB0_243
	s_and_b64 s[72:73], s[56:57], exec
	s_cselect_b32 s72, s86, s88
	s_cselect_b32 s71, s87, s89
	s_add_u32 s72, s72, s14
	s_addc_u32 s73, s71, s15
	v_lshlrev_b32_e32 v114, 1, v112
	v_mov_b32_e32 v115, v141
	v_lshl_add_u64 v[114:115], s[72:73], 0, v[114:115]
	v_lshlrev_b32_e32 v116, 1, v146
	v_mov_b32_e32 v117, v141
	v_lshl_add_u64 v[114:115], v[114:115], 0, v[116:117]
	global_store_dwordx4 v[114:115], v[96:99], off
	s_and_saveexec_b64 s[72:73], s[12:13]
	s_cbranch_execz .LBB0_242
	s_lshl_b32 s71, s47, 2
	s_add_u32 vcc_lo, s18, s71
	v_or_b32_e32 v114, s93, v100
	v_mov_b32_e32 v115, v101
	s_addc_u32 vcc_hi, s19, 0
	v_lshlrev_b64 v[114:115], 8, v[114:115]
	v_lshl_add_u64 v[114:115], vcc, 0, v[114:115]
	v_lshlrev_b32_e32 v116, 2, v146
	v_mov_b32_e32 v117, v141
	v_lshl_add_u64 v[114:115], v[114:115], 0, v[116:117]
	global_store_dwordx4 v[114:115], v[92:95], off
	global_store_dwordx4 v[114:115], v[88:91], off offset:16

.LBB0_260:
	s_andn2_b64 vcc, exec, s[14:15]
	s_cbranch_vccnz .LBB0_267
	s_or_b32 s14, s90, s94
	v_pk_mul_f32 v[88:89], v[86:87], s[44:45] op_sel_hi:[1,0]
	v_pk_mul_f32 v[90:91], v[84:85], s[44:45] op_sel_hi:[1,0]
	v_pk_mul_f32 v[92:93], v[82:83], s[44:45] op_sel_hi:[1,0]
	v_pk_mul_f32 v[94:95], v[80:81], s[44:45] op_sel_hi:[1,0]
	s_ashr_i32 s15, s14, 31
	v_cndmask_b32_e64 v93, v83, v93, s[6:7]
	v_cndmask_b32_e64 v92, v82, v92, s[6:7]
	v_cndmask_b32_e64 v95, v81, v95, s[6:7]
	v_cndmask_b32_e64 v94, v80, v94, s[6:7]
	v_cndmask_b32_e64 v89, v87, v89, s[6:7]
	v_cndmask_b32_e64 v96, v86, v88, s[6:7]
	v_cndmask_b32_e64 v88, v85, v91, s[6:7]
	v_cndmask_b32_e64 v90, v84, v90, s[6:7]
	v_cvt_pk_bf16_f32 v88, v90, v88
	v_cvt_pk_bf16_f32 v89, v96, v89
	v_cvt_pk_bf16_f32 v90, v94, v95
	v_cvt_pk_bf16_f32 v91, v92, v93
	s_lshl_b64 s[14:15], s[14:15], 19
	s_mov_b64 s[72:73], -1
	s_andn2_b64 vcc, exec, s[60:61]
	v_lshlrev_b32_e32 v92, 1, v112
	s_cbranch_vccnz .LBB0_265
	s_and_b64 s[72:73], s[56:57], exec
	s_cselect_b32 s72, s86, s88
	s_cselect_b32 s71, s87, s89
	s_add_u32 s72, s72, s14
	s_addc_u32 s73, s71, s15
	v_mov_b32_e32 v93, v141
	v_lshl_add_u64 v[94:95], s[72:73], 0, v[92:93]
	v_lshlrev_b32_e32 v96, 1, v150
	v_mov_b32_e32 v97, v141
	v_lshl_add_u64 v[94:95], v[94:95], 0, v[96:97]
	global_store_dwordx4 v[94:95], v[88:91], off
	s_and_saveexec_b64 s[72:73], s[12:13]
	s_cbranch_execz .LBB0_264
	s_lshl_b32 s12, s47, 2
	s_add_u32 s12, s18, s12
	v_or_b32_e32 v100, s94, v100
	s_addc_u32 s13, s19, 0
	v_lshlrev_b64 v[94:95], 8, v[100:101]
	v_lshl_add_u64 v[94:95], s[12:13], 0, v[94:95]
	v_lshlrev_b32_e32 v96, 2, v150
	v_mov_b32_e32 v97, v141
	v_lshl_add_u64 v[94:95], v[94:95], 0, v[96:97]
	global_store_dwordx4 v[94:95], v[84:87], off
	global_store_dwordx4 v[94:95], v[80:83], off offset:16

.LBB0_288:
	s_andn2_b64 vcc, exec, s[68:69]
	s_cbranch_vccnz .LBB0_295
	s_or_b32 s68, s90, s93
	v_pk_mul_f32 v[80:81], v[78:79], s[44:45] op_sel_hi:[1,0]
	v_pk_mul_f32 v[82:83], v[76:77], s[44:45] op_sel_hi:[1,0]
	v_pk_mul_f32 v[100:101], v[74:75], s[44:45] op_sel_hi:[1,0]
	v_pk_mul_f32 v[102:103], v[72:73], s[44:45] op_sel_hi:[1,0]
	s_ashr_i32 s69, s68, 31
	v_cndmask_b32_e64 v99, v75, v101, s[6:7]
	v_cndmask_b32_e64 v100, v74, v100, s[6:7]
	v_cndmask_b32_e64 v101, v73, v103, s[6:7]
	v_cndmask_b32_e64 v102, v72, v102, s[6:7]
	v_cndmask_b32_e64 v81, v79, v81, s[6:7]
	v_cndmask_b32_e64 v103, v78, v80, s[6:7]
	v_cndmask_b32_e64 v80, v77, v83, s[6:7]
	v_cndmask_b32_e64 v82, v76, v82, s[6:7]
	v_cvt_pk_bf16_f32 v80, v82, v80
	v_cvt_pk_bf16_f32 v81, v103, v81
	v_cvt_pk_bf16_f32 v82, v102, v101
	v_cvt_pk_bf16_f32 v83, v100, v99
	s_lshl_b64 s[68:69], s[68:69], 19
	s_andn2_b64 vcc, exec, s[60:61]
	s_mov_b64 s[70:71], -1
	s_cbranch_vccnz .LBB0_293
	s_and_b64 s[70:71], s[56:57], exec
	s_cselect_b32 s70, s86, s88
	s_cselect_b32 s71, s87, s89
	s_add_u32 s70, s70, s68
	s_addc_u32 s71, s71, s69
	v_lshlrev_b32_e32 v100, 1, v98
	v_mov_b32_e32 v101, v141
	v_lshl_add_u64 v[100:101], s[70:71], 0, v[100:101]
	v_lshlrev_b32_e32 v102, 1, v146
	v_mov_b32_e32 v103, v141
	v_lshl_add_u64 v[100:101], v[100:101], 0, v[102:103]
	global_store_dwordx4 v[100:101], v[80:83], off
	s_and_saveexec_b64 s[70:71], s[12:13]
	s_cbranch_execz .LBB0_292
	s_lshl_b32 s72, s47, 2
	s_add_u32 s72, s18, s72
	v_or_b32_e32 v100, s93, v84
	v_mov_b32_e32 v101, v85
	s_addc_u32 s73, s19, 0
	v_lshlrev_b64 v[100:101], 8, v[100:101]
	v_lshl_add_u64 v[100:101], s[72:73], 0, v[100:101]
	v_lshlrev_b32_e32 v102, 2, v146
	v_mov_b32_e32 v103, v141
	v_lshl_add_u64 v[100:101], v[100:101], 0, v[102:103]
	global_store_dwordx4 v[100:101], v[76:79], off
	global_store_dwordx4 v[100:101], v[72:75], off offset:16

.LBB0_316:
	s_andn2_b64 vcc, exec, s[14:15]
	s_cbranch_vccnz .LBB0_323
	s_or_b32 s14, s90, s94
	v_pk_mul_f32 v[72:73], v[70:71], s[44:45] op_sel_hi:[1,0]
	v_pk_mul_f32 v[74:75], v[68:69], s[44:45] op_sel_hi:[1,0]
	v_pk_mul_f32 v[76:77], v[66:67], s[44:45] op_sel_hi:[1,0]
	v_pk_mul_f32 v[78:79], v[64:65], s[44:45] op_sel_hi:[1,0]
	s_ashr_i32 s15, s14, 31
	v_cndmask_b32_e64 v77, v67, v77, s[6:7]
	v_cndmask_b32_e64 v76, v66, v76, s[6:7]
	v_cndmask_b32_e64 v79, v65, v79, s[6:7]
	v_cndmask_b32_e64 v78, v64, v78, s[6:7]
	v_cndmask_b32_e64 v73, v71, v73, s[6:7]
	v_cndmask_b32_e64 v80, v70, v72, s[6:7]
	v_cndmask_b32_e64 v72, v69, v75, s[6:7]
	v_cndmask_b32_e64 v74, v68, v74, s[6:7]
	v_cvt_pk_bf16_f32 v72, v74, v72
	v_cvt_pk_bf16_f32 v73, v80, v73
	v_cvt_pk_bf16_f32 v74, v78, v79
	v_cvt_pk_bf16_f32 v75, v76, v77
	s_lshl_b64 s[14:15], s[14:15], 19
	s_mov_b64 s[68:69], -1
	s_andn2_b64 vcc, exec, s[60:61]
	v_lshlrev_b32_e32 v76, 1, v98
	s_cbranch_vccnz .LBB0_321
	s_and_b64 s[68:69], s[56:57], exec
	s_cselect_b32 s68, s86, s88
	s_cselect_b32 s69, s87, s89
	s_add_u32 s68, s68, s14
	s_addc_u32 s69, s69, s15
	v_mov_b32_e32 v77, v141
	v_lshl_add_u64 v[78:79], s[68:69], 0, v[76:77]
	v_lshlrev_b32_e32 v80, 1, v150
	v_mov_b32_e32 v81, v141
	v_lshl_add_u64 v[78:79], v[78:79], 0, v[80:81]
	global_store_dwordx4 v[78:79], v[72:75], off
	s_and_saveexec_b64 s[68:69], s[12:13]
	s_cbranch_execz .LBB0_320
	s_lshl_b32 s12, s47, 2
	s_add_u32 s12, s18, s12
	v_or_b32_e32 v84, s94, v84
	s_addc_u32 s13, s19, 0
	v_lshlrev_b64 v[78:79], 8, v[84:85]
	v_lshl_add_u64 v[78:79], s[12:13], 0, v[78:79]
	v_lshlrev_b32_e32 v80, 2, v150
	v_mov_b32_e32 v81, v141
	v_lshl_add_u64 v[78:79], v[78:79], 0, v[80:81]
	global_store_dwordx4 v[78:79], v[68:71], off
	global_store_dwordx4 v[78:79], v[64:67], off offset:16

.LBB0_338:
	s_andn2_b64 vcc, exec, s[14:15]
	s_cbranch_vccnz .LBB0_345
	s_or_b32 s14, s75, s93
	v_pk_mul_f32 v[64:65], v[62:63], s[44:45] op_sel_hi:[1,0]
	v_pk_mul_f32 v[66:67], v[60:61], s[44:45] op_sel_hi:[1,0]
	v_pk_mul_f32 v[82:83], v[58:59], s[44:45] op_sel_hi:[1,0]
	v_pk_mul_f32 v[84:85], v[56:57], s[44:45] op_sel_hi:[1,0]
	s_ashr_i32 s15, s14, 31
	v_cndmask_b32_e64 v81, v59, v83, s[6:7]
	v_cndmask_b32_e64 v82, v58, v82, s[6:7]
	v_cndmask_b32_e64 v83, v57, v85, s[6:7]
	v_cndmask_b32_e64 v84, v56, v84, s[6:7]
	v_cndmask_b32_e64 v65, v63, v65, s[6:7]
	v_cndmask_b32_e64 v85, v62, v64, s[6:7]
	v_cndmask_b32_e64 v64, v61, v67, s[6:7]
	v_cndmask_b32_e64 v66, v60, v66, s[6:7]
	v_cvt_pk_bf16_f32 v64, v66, v64
	v_cvt_pk_bf16_f32 v65, v85, v65
	v_cvt_pk_bf16_f32 v66, v84, v83
	v_cvt_pk_bf16_f32 v67, v82, v81
	s_lshl_b64 s[14:15], s[14:15], 19
	s_andn2_b64 vcc, exec, s[60:61]
	s_mov_b64 s[72:73], -1
	s_cbranch_vccnz .LBB0_343
	s_and_b64 s[72:73], s[56:57], exec
	s_cselect_b32 s72, s86, s88
	s_cselect_b32 s71, s87, s89
	s_add_u32 s72, s72, s14
	s_addc_u32 s73, s71, s15
	v_lshlrev_b32_e32 v82, 1, v80
	v_mov_b32_e32 v83, v141
	v_lshl_add_u64 v[82:83], s[72:73], 0, v[82:83]
	v_lshlrev_b32_e32 v84, 1, v146
	v_mov_b32_e32 v85, v141
	v_lshl_add_u64 v[82:83], v[82:83], 0, v[84:85]
	global_store_dwordx4 v[82:83], v[64:67], off
	s_and_saveexec_b64 s[72:73], s[12:13]
	s_cbranch_execz .LBB0_342
	s_lshl_b32 s71, s47, 2
	s_add_u32 vcc_lo, s18, s71
	v_or_b32_e32 v82, s93, v68
	v_mov_b32_e32 v83, v69
	s_addc_u32 vcc_hi, s19, 0
	v_lshlrev_b64 v[82:83], 8, v[82:83]
	v_lshl_add_u64 v[82:83], vcc, 0, v[82:83]
	v_lshlrev_b32_e32 v84, 2, v146
	v_mov_b32_e32 v85, v141
	v_lshl_add_u64 v[82:83], v[82:83], 0, v[84:85]
	global_store_dwordx4 v[82:83], v[60:63], off
	global_store_dwordx4 v[82:83], v[56:59], off offset:16

.LBB0_360:
	s_andn2_b64 vcc, exec, s[14:15]
	s_cbranch_vccnz .LBB0_367
	s_or_b32 s14, s75, s94
	v_pk_mul_f32 v[56:57], v[54:55], s[44:45] op_sel_hi:[1,0]
	v_pk_mul_f32 v[58:59], v[52:53], s[44:45] op_sel_hi:[1,0]
	v_pk_mul_f32 v[60:61], v[50:51], s[44:45] op_sel_hi:[1,0]
	v_pk_mul_f32 v[62:63], v[48:49], s[44:45] op_sel_hi:[1,0]
	s_ashr_i32 s15, s14, 31
	v_cndmask_b32_e64 v61, v51, v61, s[6:7]
	v_cndmask_b32_e64 v60, v50, v60, s[6:7]
	v_cndmask_b32_e64 v63, v49, v63, s[6:7]
	v_cndmask_b32_e64 v62, v48, v62, s[6:7]
	v_cndmask_b32_e64 v57, v55, v57, s[6:7]
	v_cndmask_b32_e64 v64, v54, v56, s[6:7]
	v_cndmask_b32_e64 v56, v53, v59, s[6:7]
	v_cndmask_b32_e64 v58, v52, v58, s[6:7]
	v_cvt_pk_bf16_f32 v56, v58, v56
	v_cvt_pk_bf16_f32 v57, v64, v57
	v_cvt_pk_bf16_f32 v58, v62, v63
	v_cvt_pk_bf16_f32 v59, v60, v61
	s_lshl_b64 s[14:15], s[14:15], 19
	s_mov_b64 s[72:73], -1
	s_andn2_b64 vcc, exec, s[60:61]
	v_lshlrev_b32_e32 v60, 1, v80
	s_cbranch_vccnz .LBB0_365
	s_and_b64 s[72:73], s[56:57], exec
	s_cselect_b32 s72, s86, s88
	s_cselect_b32 s71, s87, s89
	s_add_u32 s72, s72, s14
	s_addc_u32 s73, s71, s15
	v_mov_b32_e32 v61, v141
	v_lshl_add_u64 v[62:63], s[72:73], 0, v[60:61]
	v_lshlrev_b32_e32 v64, 1, v150
	v_mov_b32_e32 v65, v141
	v_lshl_add_u64 v[62:63], v[62:63], 0, v[64:65]
	global_store_dwordx4 v[62:63], v[56:59], off
	s_and_saveexec_b64 s[72:73], s[12:13]
	s_cbranch_execz .LBB0_364
	s_lshl_b32 s12, s47, 2
	s_add_u32 s12, s18, s12
	v_or_b32_e32 v68, s94, v68
	s_addc_u32 s13, s19, 0
	v_lshlrev_b64 v[62:63], 8, v[68:69]
	v_lshl_add_u64 v[62:63], s[12:13], 0, v[62:63]
	v_lshlrev_b32_e32 v64, 2, v150
	v_mov_b32_e32 v65, v141
	v_lshl_add_u64 v[62:63], v[62:63], 0, v[64:65]
	global_store_dwordx4 v[62:63], v[52:55], off
	global_store_dwordx4 v[62:63], v[48:51], off offset:16

.LBB0_382:
	s_andn2_b64 vcc, exec, s[14:15]
	s_cbranch_vccnz .LBB0_389
	s_or_b32 s14, s75, s93
	v_pk_mul_f32 v[48:49], v[46:47], s[44:45] op_sel_hi:[1,0]
	v_pk_mul_f32 v[50:51], v[44:45], s[44:45] op_sel_hi:[1,0]
	v_pk_mul_f32 v[66:67], v[42:43], s[44:45] op_sel_hi:[1,0]
	v_pk_mul_f32 v[68:69], v[40:41], s[44:45] op_sel_hi:[1,0]
	s_ashr_i32 s15, s14, 31
	v_cndmask_b32_e64 v65, v43, v67, s[6:7]
	v_cndmask_b32_e64 v66, v42, v66, s[6:7]
	v_cndmask_b32_e64 v67, v41, v69, s[6:7]
	v_cndmask_b32_e64 v68, v40, v68, s[6:7]
	v_cndmask_b32_e64 v49, v47, v49, s[6:7]
	v_cndmask_b32_e64 v69, v46, v48, s[6:7]
	v_cndmask_b32_e64 v48, v45, v51, s[6:7]
	v_cndmask_b32_e64 v50, v44, v50, s[6:7]
	v_cvt_pk_bf16_f32 v48, v50, v48
	v_cvt_pk_bf16_f32 v49, v69, v49
	v_cvt_pk_bf16_f32 v50, v68, v67
	v_cvt_pk_bf16_f32 v51, v66, v65
	s_lshl_b64 s[14:15], s[14:15], 19
	s_andn2_b64 vcc, exec, s[60:61]
	s_mov_b64 s[72:73], -1
	s_cbranch_vccnz .LBB0_387
	s_and_b64 s[72:73], s[56:57], exec
	s_cselect_b32 s72, s86, s88
	s_cselect_b32 s71, s87, s89
	s_add_u32 s72, s72, s14
	s_addc_u32 s73, s71, s15
	v_lshlrev_b32_e32 v66, 1, v64
	v_mov_b32_e32 v67, v141
	v_lshl_add_u64 v[66:67], s[72:73], 0, v[66:67]
	v_lshlrev_b32_e32 v68, 1, v146
	v_mov_b32_e32 v69, v141
	v_lshl_add_u64 v[66:67], v[66:67], 0, v[68:69]
	global_store_dwordx4 v[66:67], v[48:51], off
	s_and_saveexec_b64 s[72:73], s[12:13]
	s_cbranch_execz .LBB0_386
	s_lshl_b32 s71, s47, 2
	s_add_u32 vcc_lo, s18, s71
	v_or_b32_e32 v66, s93, v52
	v_mov_b32_e32 v67, v53
	s_addc_u32 vcc_hi, s19, 0
	v_lshlrev_b64 v[66:67], 8, v[66:67]
	v_lshl_add_u64 v[66:67], vcc, 0, v[66:67]
	v_lshlrev_b32_e32 v68, 2, v146
	v_mov_b32_e32 v69, v141
	v_lshl_add_u64 v[66:67], v[66:67], 0, v[68:69]
	global_store_dwordx4 v[66:67], v[44:47], off
	global_store_dwordx4 v[66:67], v[40:43], off offset:16

.LBB0_404:
	s_andn2_b64 vcc, exec, s[14:15]
	s_cbranch_vccnz .LBB0_411
	s_or_b32 s14, s75, s94
	v_pk_mul_f32 v[40:41], v[38:39], s[44:45] op_sel_hi:[1,0]
	v_pk_mul_f32 v[42:43], v[36:37], s[44:45] op_sel_hi:[1,0]
	v_pk_mul_f32 v[44:45], v[34:35], s[44:45] op_sel_hi:[1,0]
	v_pk_mul_f32 v[46:47], v[32:33], s[44:45] op_sel_hi:[1,0]
	s_ashr_i32 s15, s14, 31
	v_cndmask_b32_e64 v45, v35, v45, s[6:7]
	v_cndmask_b32_e64 v44, v34, v44, s[6:7]
	v_cndmask_b32_e64 v47, v33, v47, s[6:7]
	v_cndmask_b32_e64 v46, v32, v46, s[6:7]
	v_cndmask_b32_e64 v41, v39, v41, s[6:7]
	v_cndmask_b32_e64 v48, v38, v40, s[6:7]
	v_cndmask_b32_e64 v40, v37, v43, s[6:7]
	v_cndmask_b32_e64 v42, v36, v42, s[6:7]
	v_cvt_pk_bf16_f32 v40, v42, v40
	v_cvt_pk_bf16_f32 v41, v48, v41
	v_cvt_pk_bf16_f32 v42, v46, v47
	v_cvt_pk_bf16_f32 v43, v44, v45
	s_lshl_b64 s[14:15], s[14:15], 19
	s_mov_b64 s[72:73], -1
	s_andn2_b64 vcc, exec, s[60:61]
	v_lshlrev_b32_e32 v44, 1, v64
	s_cbranch_vccnz .LBB0_409
	s_and_b64 s[72:73], s[56:57], exec
	s_cselect_b32 s72, s86, s88
	s_cselect_b32 s71, s87, s89
	s_add_u32 s72, s72, s14
	s_addc_u32 s73, s71, s15
	v_mov_b32_e32 v45, v141
	v_lshl_add_u64 v[46:47], s[72:73], 0, v[44:45]
	v_lshlrev_b32_e32 v48, 1, v150
	v_mov_b32_e32 v49, v141
	v_lshl_add_u64 v[46:47], v[46:47], 0, v[48:49]
	global_store_dwordx4 v[46:47], v[40:43], off
	s_and_saveexec_b64 s[72:73], s[12:13]
	s_cbranch_execz .LBB0_408
	s_lshl_b32 s12, s47, 2
	s_add_u32 s12, s18, s12
	v_or_b32_e32 v52, s94, v52
	s_addc_u32 s13, s19, 0
	v_lshlrev_b64 v[46:47], 8, v[52:53]
	v_lshl_add_u64 v[46:47], s[12:13], 0, v[46:47]
	v_lshlrev_b32_e32 v48, 2, v150
	v_mov_b32_e32 v49, v141
	v_lshl_add_u64 v[46:47], v[46:47], 0, v[48:49]
	global_store_dwordx4 v[46:47], v[36:39], off
	global_store_dwordx4 v[46:47], v[32:35], off offset:16

.LBB0_426:
	s_andn2_b64 vcc, exec, s[14:15]
	s_cbranch_vccnz .LBB0_433
	s_or_b32 s14, s75, s93
	v_pk_mul_f32 v[32:33], v[30:31], s[44:45] op_sel_hi:[1,0]
	v_pk_mul_f32 v[34:35], v[28:29], s[44:45] op_sel_hi:[1,0]
	v_pk_mul_f32 v[50:51], v[26:27], s[44:45] op_sel_hi:[1,0]
	v_pk_mul_f32 v[52:53], v[24:25], s[44:45] op_sel_hi:[1,0]
	s_ashr_i32 s15, s14, 31
	v_cndmask_b32_e64 v49, v27, v51, s[6:7]
	v_cndmask_b32_e64 v50, v26, v50, s[6:7]
	v_cndmask_b32_e64 v51, v25, v53, s[6:7]
	v_cndmask_b32_e64 v52, v24, v52, s[6:7]
	v_cndmask_b32_e64 v33, v31, v33, s[6:7]
	v_cndmask_b32_e64 v53, v30, v32, s[6:7]
	v_cndmask_b32_e64 v32, v29, v35, s[6:7]
	v_cndmask_b32_e64 v34, v28, v34, s[6:7]
	v_cvt_pk_bf16_f32 v32, v34, v32
	v_cvt_pk_bf16_f32 v33, v53, v33
	v_cvt_pk_bf16_f32 v34, v52, v51
	v_cvt_pk_bf16_f32 v35, v50, v49
	s_lshl_b64 s[14:15], s[14:15], 19
	s_andn2_b64 vcc, exec, s[60:61]
	s_mov_b64 s[72:73], -1
	s_cbranch_vccnz .LBB0_431
	s_and_b64 s[72:73], s[56:57], exec
	s_cselect_b32 s72, s86, s88
	s_cselect_b32 s71, s87, s89
	s_add_u32 s72, s72, s14
	s_addc_u32 s73, s71, s15
	v_lshlrev_b32_e32 v50, 1, v48
	v_mov_b32_e32 v51, v141
	v_lshl_add_u64 v[50:51], s[72:73], 0, v[50:51]
	v_lshlrev_b32_e32 v52, 1, v146
	v_mov_b32_e32 v53, v141
	v_lshl_add_u64 v[50:51], v[50:51], 0, v[52:53]
	global_store_dwordx4 v[50:51], v[32:35], off
	s_and_saveexec_b64 s[72:73], s[12:13]
	s_cbranch_execz .LBB0_430
	s_lshl_b32 s71, s47, 2
	s_add_u32 vcc_lo, s18, s71
	v_or_b32_e32 v50, s93, v36
	v_mov_b32_e32 v51, v37
	s_addc_u32 vcc_hi, s19, 0
	v_lshlrev_b64 v[50:51], 8, v[50:51]
	v_lshl_add_u64 v[50:51], vcc, 0, v[50:51]
	v_lshlrev_b32_e32 v52, 2, v146
	v_mov_b32_e32 v53, v141
	v_lshl_add_u64 v[50:51], v[50:51], 0, v[52:53]
	global_store_dwordx4 v[50:51], v[28:31], off
	global_store_dwordx4 v[50:51], v[24:27], off offset:16

.LBB0_448:
	s_andn2_b64 vcc, exec, s[14:15]
	s_cbranch_vccnz .LBB0_455
	s_or_b32 s14, s75, s94
	v_pk_mul_f32 v[24:25], v[22:23], s[44:45] op_sel_hi:[1,0]
	v_pk_mul_f32 v[26:27], v[20:21], s[44:45] op_sel_hi:[1,0]
	v_pk_mul_f32 v[28:29], v[18:19], s[44:45] op_sel_hi:[1,0]
	v_pk_mul_f32 v[30:31], v[16:17], s[44:45] op_sel_hi:[1,0]
	s_ashr_i32 s15, s14, 31
	v_cndmask_b32_e64 v29, v19, v29, s[6:7]
	v_cndmask_b32_e64 v28, v18, v28, s[6:7]
	v_cndmask_b32_e64 v31, v17, v31, s[6:7]
	v_cndmask_b32_e64 v30, v16, v30, s[6:7]
	v_cndmask_b32_e64 v25, v23, v25, s[6:7]
	v_cndmask_b32_e64 v32, v22, v24, s[6:7]
	v_cndmask_b32_e64 v24, v21, v27, s[6:7]
	v_cndmask_b32_e64 v26, v20, v26, s[6:7]
	v_cvt_pk_bf16_f32 v24, v26, v24
	v_cvt_pk_bf16_f32 v25, v32, v25
	v_cvt_pk_bf16_f32 v26, v30, v31
	v_cvt_pk_bf16_f32 v27, v28, v29
	s_lshl_b64 s[14:15], s[14:15], 19
	s_mov_b64 s[66:67], -1
	s_andn2_b64 vcc, exec, s[60:61]
	v_lshlrev_b32_e32 v28, 1, v48
	s_cbranch_vccnz .LBB0_453
	s_and_b64 s[66:67], s[56:57], exec
	s_cselect_b32 s66, s86, s88
	s_cselect_b32 s67, s87, s89
	s_add_u32 s66, s66, s14
	s_addc_u32 s67, s67, s15
	v_mov_b32_e32 v29, v141
	v_lshl_add_u64 v[30:31], s[66:67], 0, v[28:29]
	v_lshlrev_b32_e32 v32, 1, v150
	v_mov_b32_e32 v33, v141
	v_lshl_add_u64 v[30:31], v[30:31], 0, v[32:33]
	global_store_dwordx4 v[30:31], v[24:27], off
	s_and_saveexec_b64 s[66:67], s[12:13]
	s_cbranch_execz .LBB0_452
	s_lshl_b32 s12, s47, 2
	s_add_u32 s12, s18, s12
	v_or_b32_e32 v36, s94, v36
	s_addc_u32 s13, s19, 0
	v_lshlrev_b64 v[30:31], 8, v[36:37]
	v_lshl_add_u64 v[30:31], s[12:13], 0, v[30:31]
	v_lshlrev_b32_e32 v32, 2, v150
	v_mov_b32_e32 v33, v141
	v_lshl_add_u64 v[30:31], v[30:31], 0, v[32:33]
	global_store_dwordx4 v[30:31], v[20:23], off
	global_store_dwordx4 v[30:31], v[16:19], off offset:16

.LBB0_476:
	s_andn2_b64 vcc, exec, s[64:65]
	s_cbranch_vccnz .LBB0_483
	s_or_b32 s0, s75, s93
	v_pk_mul_f32 v[16:17], v[14:15], s[44:45] op_sel_hi:[1,0]
	v_pk_mul_f32 v[18:19], v[12:13], s[44:45] op_sel_hi:[1,0]
	v_pk_mul_f32 v[34:35], v[10:11], s[44:45] op_sel_hi:[1,0]
	v_pk_mul_f32 v[38:39], v[8:9], s[44:45] op_sel_hi:[1,0]
	s_ashr_i32 s1, s0, 31
	v_cndmask_b32_e64 v35, v11, v35, s[6:7]
	v_cndmask_b32_e64 v34, v10, v34, s[6:7]
	v_cndmask_b32_e64 v37, v9, v39, s[6:7]
	v_cndmask_b32_e64 v38, v8, v38, s[6:7]
	v_cndmask_b32_e64 v17, v15, v17, s[6:7]
	v_cndmask_b32_e64 v39, v14, v16, s[6:7]
	v_cndmask_b32_e64 v16, v13, v19, s[6:7]
	v_cndmask_b32_e64 v18, v12, v18, s[6:7]
	v_cvt_pk_bf16_f32 v16, v18, v16
	v_cvt_pk_bf16_f32 v17, v39, v17
	v_cvt_pk_bf16_f32 v18, v38, v37
	v_cvt_pk_bf16_f32 v19, v34, v35
	s_lshl_b64 s[64:65], s[0:1], 19
	s_mov_b64 s[66:67], -1
	s_andn2_b64 vcc, exec, s[60:61]
	v_lshlrev_b32_e32 v34, 1, v146
	s_cbranch_vccnz .LBB0_481
	s_and_b64 s[0:1], s[56:57], exec
	s_cselect_b32 s0, s86, s88
	s_cselect_b32 s1, s87, s89
	s_add_u32 s0, s0, s64
	s_addc_u32 s1, s1, s65
	v_lshlrev_b32_e32 v140, 1, v36
	v_lshl_add_u64 v[38:39], s[0:1], 0, v[140:141]
	v_mov_b32_e32 v35, v141
	v_lshl_add_u64 v[38:39], v[38:39], 0, v[34:35]
	global_store_dwordx4 v[38:39], v[16:19], off
	s_and_saveexec_b64 s[66:67], s[12:13]
	s_cbranch_execz .LBB0_480
	s_lshl_b32 s0, s47, 2
	s_add_u32 s0, s18, s0
	v_or_b32_e32 v38, s93, v20
	v_mov_b32_e32 v39, v21
	s_addc_u32 s1, s19, 0
	v_lshlrev_b64 v[38:39], 8, v[38:39]
	v_lshl_add_u64 v[38:39], s[0:1], 0, v[38:39]
	v_lshlrev_b32_e32 v140, 2, v146
	v_lshl_add_u64 v[38:39], v[38:39], 0, v[140:141]
	global_store_dwordx4 v[38:39], v[12:15], off
	global_store_dwordx4 v[38:39], v[8:11], off offset:16

.LBB0_504:
	s_andn2_b64 vcc, exec, s[10:11]
	s_cbranch_vccnz .LBB0_511
	s_or_b32 s0, s75, s94
	v_pk_mul_f32 v[8:9], v[6:7], s[44:45] op_sel_hi:[1,0]
	v_pk_mul_f32 v[10:11], v[4:5], s[44:45] op_sel_hi:[1,0]
	v_pk_mul_f32 v[12:13], v[2:3], s[44:45] op_sel_hi:[1,0]
	v_pk_mul_f32 v[14:15], v[0:1], s[44:45] op_sel_hi:[1,0]
	s_ashr_i32 s1, s0, 31
	v_cndmask_b32_e64 v13, v3, v13, s[6:7]
	v_cndmask_b32_e64 v12, v2, v12, s[6:7]
	v_cndmask_b32_e64 v15, v1, v15, s[6:7]
	v_cndmask_b32_e64 v14, v0, v14, s[6:7]
	v_cndmask_b32_e64 v9, v7, v9, s[6:7]
	v_cndmask_b32_e64 v16, v6, v8, s[6:7]
	v_cndmask_b32_e64 v8, v5, v11, s[6:7]
	v_cndmask_b32_e64 v10, v4, v10, s[6:7]
	v_cvt_pk_bf16_f32 v8, v10, v8
	v_cvt_pk_bf16_f32 v9, v16, v9
	v_cvt_pk_bf16_f32 v10, v14, v15
	v_cvt_pk_bf16_f32 v11, v12, v13
	s_lshl_b64 s[6:7], s[0:1], 19
	s_mov_b64 s[10:11], -1
	s_and_b64 vcc, exec, s[8:9]
	v_lshlrev_b32_e32 v140, 1, v36
	v_lshlrev_b32_e32 v12, 1, v150
	s_cbranch_vccnz .LBB0_509
	s_and_b64 s[0:1], s[56:57], exec
	s_cselect_b32 s0, s86, s88
	s_cselect_b32 s1, s87, s89
	s_add_u32 s0, s0, s6
	s_addc_u32 s1, s1, s7
	v_lshl_add_u64 v[14:15], s[0:1], 0, v[140:141]
	v_mov_b32_e32 v13, v141
	v_lshl_add_u64 v[14:15], v[14:15], 0, v[12:13]
	global_store_dwordx4 v[14:15], v[8:11], off
	s_and_saveexec_b64 s[8:9], s[12:13]
	s_cbranch_execz .LBB0_508
	s_lshl_b32 s0, s47, 2
	s_add_u32 s0, s18, s0
	v_or_b32_e32 v20, s94, v20
	s_addc_u32 s1, s19, 0
	v_lshlrev_b64 v[14:15], 8, v[20:21]
	v_lshl_add_u64 v[14:15], s[0:1], 0, v[14:15]
	v_lshlrev_b32_e32 v16, 2, v150
	v_mov_b32_e32 v17, v141
	v_lshl_add_u64 v[14:15], v[14:15], 0, v[16:17]
	global_store_dwordx4 v[14:15], v[4:7], off
	global_store_dwordx4 v[14:15], v[0:3], off offset:16

.Lssd0_tail:
	s_or_b64 exec, exec, s[14:15]
	s_add_i32 s0, s0, 1
	s_add_i32 s1, s1, 4
	s_waitcnt lgkmcnt(0)
	v_lshl_add_u64 v[52:53], v[50:51], 0, s[8:9]
	s_add_u32 s8, s8, 0x8000
	s_addc_u32 s9, s9, 0
	v_add_co_u32_e32 v52, vcc, 0x2fb35000, v52
	s_add_u32 s12, s12, 4
	s_nop 0
	v_addc_co_u32_e32 v53, vcc, 0, v53, vcc
	s_addc_u32 s13, s13, 0
	global_store_dwordx4 v[52:53], v[32:35], off
	global_store_dwordx4 v[52:53], v[36:39], off offset:16
	global_store_dwordx4 v[52:53], v[40:43], off offset:32
	global_store_dwordx4 v[52:53], v[44:47], off offset:48
	s_add_u32 s10, s10, 4
	s_addc_u32 s11, s11, 0
	v_add_u32_e32 v64, 0x100, v64
	s_cmp_eq_u32 s8, 0x60000
	s_cbranch_scc1 .LBB0_695

.Lssd1_tail:
	s_or_b64 exec, exec, s[14:15]
	s_add_i32 s0, s0, 1
	s_add_i32 s1, s1, 4
	s_waitcnt lgkmcnt(0)
	v_lshl_add_u64 v[52:53], v[50:51], 0, s[8:9]
	s_add_u32 s8, s8, 0x8000
	s_addc_u32 s9, s9, 0
	v_add_co_u32_e32 v52, vcc, 0x2fb35000, v52
	s_add_u32 s12, s12, 4
	s_nop 0
	v_addc_co_u32_e32 v53, vcc, 0, v53, vcc
	s_addc_u32 s13, s13, 0
	global_store_dwordx4 v[52:53], v[4:7], off
	global_store_dwordx4 v[52:53], v[8:11], off offset:16
	global_store_dwordx4 v[52:53], v[12:15], off offset:32
	global_store_dwordx4 v[52:53], v[0:3], off offset:48
	s_add_u32 s10, s10, 4
	s_addc_u32 s11, s11, 0
	v_add_u32_e32 v64, 0x100, v64
	s_cmp_eq_u32 s8, 0x60000
	s_cbranch_scc1 .LBB0_695

.Lssd2_tail:
	s_or_b64 exec, exec, s[14:15]
	s_add_i32 s0, s0, 1
	s_add_i32 s1, s1, 4
	s_waitcnt lgkmcnt(0)
	v_lshl_add_u64 v[52:53], v[50:51], 0, s[8:9]
	s_add_u32 s8, s8, 0x8000
	s_addc_u32 s9, s9, 0
	v_add_co_u32_e32 v52, vcc, 0x2fb35000, v52
	s_add_u32 s12, s12, 4
	s_nop 0
	v_addc_co_u32_e32 v53, vcc, 0, v53, vcc
	s_addc_u32 s13, s13, 0
	global_store_dwordx4 v[52:53], v[16:19], off
	global_store_dwordx4 v[52:53], v[20:23], off offset:16
	global_store_dwordx4 v[52:53], v[28:31], off offset:32
	global_store_dwordx4 v[52:53], v[24:27], off offset:48
	s_add_u32 s10, s10, 4
	s_addc_u32 s11, s11, 0
	v_add_u32_e32 v64, 0x100, v64
	s_cmp_eq_u32 s8, 0x60000
	s_cbranch_scc1 .LBB0_695
	s_branch .Lssd_body0
